# ret_scan/hg_scan: the 4 serialized load->wait->store trips unrolled with two alternating register sets so the next trip's loads are in flight while the current one is processed; on top of previous
# speedup vs baseline: 1.0068x; 1.0055x over previous
.LBB0_210:
	s_add_i32 s13, s12, 7
	v_mov_b32_e32 v0, s13
	v_mov_b32_e32 v1, s7
	v_cndmask_b32_e32 v0, v0, v1, vcc
	v_add_u32_e32 v0, v0, v43
	v_ashrrev_i32_e32 v1, 31, v0
	v_lshlrev_b64 v[0:1], 14, v[0:1]
	s_add_i32 s13, s12, 6
	s_add_i32 s14, s7, 1
	v_lshl_add_u64 v[34:35], v[26:27], 0, v[0:1]
	v_mov_b32_e32 v4, s13
	v_mov_b32_e32 v5, s14
	global_load_dwordx4 v[0:3], v[34:35], off
	v_cndmask_b32_e32 v4, v4, v5, vcc
	v_add_u32_e32 v4, v4, v43
	v_ashrrev_i32_e32 v5, 31, v4
	v_lshlrev_b64 v[4:5], 14, v[4:5]
	v_lshl_add_u64 v[36:37], v[26:27], 0, v[4:5]
	s_add_i32 s13, s12, 5
	s_add_i32 s14, s7, 2
	global_load_dwordx4 v[4:7], v[36:37], off
	v_mov_b32_e32 v8, s13
	v_mov_b32_e32 v9, s14
	v_cndmask_b32_e32 v8, v8, v9, vcc
	v_add_u32_e32 v8, v8, v43
	v_ashrrev_i32_e32 v9, 31, v8
	v_lshlrev_b64 v[8:9], 14, v[8:9]
	v_lshl_add_u64 v[38:39], v[26:27], 0, v[8:9]
	s_add_i32 s13, s12, 4
	s_add_i32 s14, s7, 3
	global_load_dwordx4 v[8:11], v[38:39], off
	v_mov_b32_e32 v12, s13
	v_mov_b32_e32 v13, s14
	v_cndmask_b32_e32 v12, v12, v13, vcc
	v_add_u32_e32 v12, v12, v43
	v_ashrrev_i32_e32 v13, 31, v12
	v_lshlrev_b64 v[12:13], 14, v[12:13]
	v_lshl_add_u64 v[40:41], v[26:27], 0, v[12:13]
	s_add_i32 s13, s12, 3
	s_add_i32 s14, s7, 4
	global_load_dwordx4 v[12:15], v[40:41], off
	v_mov_b32_e32 v16, s13
	v_mov_b32_e32 v17, s14
	v_cndmask_b32_e32 v16, v16, v17, vcc
	v_add_u32_e32 v16, v16, v43
	v_ashrrev_i32_e32 v17, 31, v16
	v_lshlrev_b64 v[16:17], 14, v[16:17]
	v_lshl_add_u64 v[60:61], v[26:27], 0, v[16:17]
	s_add_i32 s13, s12, 2
	s_add_i32 s14, s7, 5
	global_load_dwordx4 v[16:19], v[60:61], off
	v_mov_b32_e32 v44, s13
	v_mov_b32_e32 v45, s14
	v_cndmask_b32_e32 v44, v44, v45, vcc
	v_add_u32_e32 v44, v44, v43
	v_ashrrev_i32_e32 v45, 31, v44
	v_lshlrev_b64 v[44:45], 14, v[44:45]
	v_lshl_add_u64 v[62:63], v[26:27], 0, v[44:45]
	s_add_i32 s13, s12, 1
	s_add_i32 s14, s7, 6
	global_load_dwordx4 v[44:47], v[62:63], off
	v_mov_b32_e32 v48, s13
	v_mov_b32_e32 v49, s14
	v_cndmask_b32_e32 v48, v48, v49, vcc
	v_add_u32_e32 v48, v48, v43
	v_ashrrev_i32_e32 v49, 31, v48
	v_lshlrev_b64 v[48:49], 14, v[48:49]
	v_lshl_add_u64 v[64:65], v[26:27], 0, v[48:49]
	s_add_i32 s13, s7, 7
	global_load_dwordx4 v[48:51], v[64:65], off
	v_mov_b32_e32 v52, s12
	v_mov_b32_e32 v53, s13
	v_cndmask_b32_e32 v52, v52, v53, vcc
	v_add_u32_e32 v52, v52, v43
	v_ashrrev_i32_e32 v53, 31, v52
	v_lshlrev_b64 v[52:53], 14, v[52:53]
	v_lshl_add_u64 v[66:67], v[26:27], 0, v[52:53]
	global_load_dwordx4 v[52:55], v[66:67], off
	v_cvt_pk_bf16_f32 v56, v28, v29
	v_cvt_pk_bf16_f32 v57, v30, v31
	v_cvt_pk_bf16_f32 v58, v32, v33
	v_cvt_pk_bf16_f32 v59, v22, v23
	global_store_dwordx4 v[34:35], v[56:59], off
	s_add_i32 s12, s12, -8
	s_add_i32 s13, s7, 8
	s_mov_b32 s7, s13
	s_add_i32 s13, s12, 7
	v_mov_b32_e32 v72, s13
	v_mov_b32_e32 v73, s7
	v_cndmask_b32_e32 v72, v72, v73, vcc
	v_add_u32_e32 v72, v72, v43
	v_ashrrev_i32_e32 v73, 31, v72
	v_lshlrev_b64 v[72:73], 14, v[72:73]
	s_add_i32 s13, s12, 6
	s_add_i32 s14, s7, 1
	v_lshl_add_u64 v[106:107], v[26:27], 0, v[72:73]
	v_mov_b32_e32 v76, s13
	v_mov_b32_e32 v77, s14
	global_load_dwordx4 v[72:75], v[106:107], off
	v_cndmask_b32_e32 v76, v76, v77, vcc
	v_add_u32_e32 v76, v76, v43
	v_ashrrev_i32_e32 v77, 31, v76
	v_lshlrev_b64 v[76:77], 14, v[76:77]
	v_lshl_add_u64 v[108:109], v[26:27], 0, v[76:77]
	s_add_i32 s13, s12, 5
	s_add_i32 s14, s7, 2
	global_load_dwordx4 v[76:79], v[108:109], off
	v_mov_b32_e32 v80, s13
	v_mov_b32_e32 v81, s14
	v_cndmask_b32_e32 v80, v80, v81, vcc
	v_add_u32_e32 v80, v80, v43
	v_ashrrev_i32_e32 v81, 31, v80
	v_lshlrev_b64 v[80:81], 14, v[80:81]
	v_lshl_add_u64 v[110:111], v[26:27], 0, v[80:81]
	s_add_i32 s13, s12, 4
	s_add_i32 s14, s7, 3
	global_load_dwordx4 v[80:83], v[110:111], off
	v_mov_b32_e32 v84, s13
	v_mov_b32_e32 v85, s14
	v_cndmask_b32_e32 v84, v84, v85, vcc
	v_add_u32_e32 v84, v84, v43
	v_ashrrev_i32_e32 v85, 31, v84
	v_lshlrev_b64 v[84:85], 14, v[84:85]
	v_lshl_add_u64 v[112:113], v[26:27], 0, v[84:85]
	s_add_i32 s13, s12, 3
	s_add_i32 s14, s7, 4
	global_load_dwordx4 v[84:87], v[112:113], off
	v_mov_b32_e32 v88, s13
	v_mov_b32_e32 v89, s14
	v_cndmask_b32_e32 v88, v88, v89, vcc
	v_add_u32_e32 v88, v88, v43
	v_ashrrev_i32_e32 v89, 31, v88
	v_lshlrev_b64 v[88:89], 14, v[88:89]
	v_lshl_add_u64 v[144:145], v[26:27], 0, v[88:89]
	s_add_i32 s13, s12, 2
	s_add_i32 s14, s7, 5
	global_load_dwordx4 v[88:91], v[144:145], off
	v_mov_b32_e32 v116, s13
	v_mov_b32_e32 v117, s14
	v_cndmask_b32_e32 v116, v116, v117, vcc
	v_add_u32_e32 v116, v116, v43
	v_ashrrev_i32_e32 v117, 31, v116
	v_lshlrev_b64 v[116:117], 14, v[116:117]
	v_lshl_add_u64 v[146:147], v[26:27], 0, v[116:117]
	s_add_i32 s13, s12, 1
	s_add_i32 s14, s7, 6
	global_load_dwordx4 v[116:119], v[146:147], off
	v_mov_b32_e32 v120, s13
	v_mov_b32_e32 v121, s14
	v_cndmask_b32_e32 v120, v120, v121, vcc
	v_add_u32_e32 v120, v120, v43
	v_ashrrev_i32_e32 v121, 31, v120
	v_lshlrev_b64 v[120:121], 14, v[120:121]
	v_lshl_add_u64 v[148:149], v[26:27], 0, v[120:121]
	s_add_i32 s13, s7, 7
	global_load_dwordx4 v[120:123], v[148:149], off
	v_mov_b32_e32 v124, s12
	v_mov_b32_e32 v125, s13
	v_cndmask_b32_e32 v124, v124, v125, vcc
	v_add_u32_e32 v124, v124, v43
	v_ashrrev_i32_e32 v125, 31, v124
	v_lshlrev_b64 v[124:125], 14, v[124:125]
	v_lshl_add_u64 v[150:151], v[26:27], 0, v[124:125]
	global_load_dwordx4 v[124:127], v[150:151], off
	s_waitcnt vmcnt(9)
	v_lshlrev_b32_e32 v34, 16, v0
	v_and_b32_e32 v35, 0xffff0000, v0
	v_lshlrev_b32_e32 v0, 16, v1
	v_and_b32_e32 v1, 0xffff0000, v1
	v_pk_fma_f32 v[30:31], v[24:25], v[30:31], v[0:1]
	v_lshlrev_b32_e32 v0, 16, v2
	v_and_b32_e32 v1, 0xffff0000, v2
	v_pk_fma_f32 v[32:33], v[24:25], v[32:33], v[0:1]
	v_lshlrev_b32_e32 v0, 16, v3
	v_and_b32_e32 v1, 0xffff0000, v3
	v_pk_fma_f32 v[28:29], v[24:25], v[28:29], v[34:35]
	v_pk_fma_f32 v[22:23], v[24:25], v[22:23], v[0:1]
	v_cvt_pk_bf16_f32 v0, v28, v29
	v_cvt_pk_bf16_f32 v1, v30, v31
	v_cvt_pk_bf16_f32 v2, v32, v33
	v_cvt_pk_bf16_f32 v3, v22, v23
	global_store_dwordx4 v[36:37], v[0:3], off
	s_nop 1
	v_lshlrev_b32_e32 v0, 16, v4
	v_and_b32_e32 v1, 0xffff0000, v4
	v_pk_fma_f32 v[28:29], v[24:25], v[28:29], v[0:1]
	v_lshlrev_b32_e32 v0, 16, v5
	v_and_b32_e32 v1, 0xffff0000, v5
	v_pk_fma_f32 v[4:5], v[24:25], v[30:31], v[0:1]
	v_lshlrev_b32_e32 v0, 16, v6
	v_and_b32_e32 v1, 0xffff0000, v6
	v_pk_fma_f32 v[30:31], v[24:25], v[32:33], v[0:1]
	v_lshlrev_b32_e32 v0, 16, v7
	v_and_b32_e32 v1, 0xffff0000, v7
	v_pk_fma_f32 v[6:7], v[24:25], v[22:23], v[0:1]
	v_cvt_pk_bf16_f32 v0, v28, v29
	v_cvt_pk_bf16_f32 v1, v4, v5
	v_cvt_pk_bf16_f32 v2, v30, v31
	v_cvt_pk_bf16_f32 v3, v6, v7
	global_store_dwordx4 v[38:39], v[0:3], off
	s_nop 1
	v_lshlrev_b32_e32 v0, 16, v8
	v_and_b32_e32 v1, 0xffff0000, v8
	v_pk_fma_f32 v[22:23], v[24:25], v[28:29], v[0:1]
	v_lshlrev_b32_e32 v0, 16, v9
	v_and_b32_e32 v1, 0xffff0000, v9
	v_pk_fma_f32 v[4:5], v[24:25], v[4:5], v[0:1]
	v_lshlrev_b32_e32 v0, 16, v10
	v_and_b32_e32 v1, 0xffff0000, v10
	v_pk_fma_f32 v[8:9], v[24:25], v[30:31], v[0:1]
	v_lshlrev_b32_e32 v0, 16, v11
	v_and_b32_e32 v1, 0xffff0000, v11
	v_pk_fma_f32 v[6:7], v[24:25], v[6:7], v[0:1]
	v_cvt_pk_bf16_f32 v0, v22, v23
	v_cvt_pk_bf16_f32 v1, v4, v5
	v_cvt_pk_bf16_f32 v2, v8, v9
	v_cvt_pk_bf16_f32 v3, v6, v7
	global_store_dwordx4 v[40:41], v[0:3], off
	s_nop 1
	v_lshlrev_b32_e32 v0, 16, v12
	v_and_b32_e32 v1, 0xffff0000, v12
	v_pk_fma_f32 v[10:11], v[24:25], v[22:23], v[0:1]
	v_lshlrev_b32_e32 v0, 16, v13
	v_and_b32_e32 v1, 0xffff0000, v13
	v_pk_fma_f32 v[4:5], v[24:25], v[4:5], v[0:1]
	v_lshlrev_b32_e32 v0, 16, v14
	v_and_b32_e32 v1, 0xffff0000, v14
	v_pk_fma_f32 v[8:9], v[24:25], v[8:9], v[0:1]
	v_lshlrev_b32_e32 v0, 16, v15
	v_and_b32_e32 v1, 0xffff0000, v15
	v_pk_fma_f32 v[6:7], v[24:25], v[6:7], v[0:1]
	v_cvt_pk_bf16_f32 v0, v10, v11
	v_cvt_pk_bf16_f32 v1, v4, v5
	v_cvt_pk_bf16_f32 v2, v8, v9
	v_cvt_pk_bf16_f32 v3, v6, v7
	global_store_dwordx4 v[60:61], v[0:3], off
	s_nop 1
	v_lshlrev_b32_e32 v0, 16, v16
	v_and_b32_e32 v1, 0xffff0000, v16
	v_pk_fma_f32 v[10:11], v[24:25], v[10:11], v[0:1]
	v_lshlrev_b32_e32 v0, 16, v17
	v_and_b32_e32 v1, 0xffff0000, v17
	v_pk_fma_f32 v[4:5], v[24:25], v[4:5], v[0:1]
	v_lshlrev_b32_e32 v0, 16, v18
	v_and_b32_e32 v1, 0xffff0000, v18
	v_pk_fma_f32 v[8:9], v[24:25], v[8:9], v[0:1]
	v_lshlrev_b32_e32 v0, 16, v19
	v_and_b32_e32 v1, 0xffff0000, v19
	v_pk_fma_f32 v[6:7], v[24:25], v[6:7], v[0:1]
	v_cvt_pk_bf16_f32 v0, v10, v11
	v_cvt_pk_bf16_f32 v1, v4, v5
	v_cvt_pk_bf16_f32 v2, v8, v9
	v_cvt_pk_bf16_f32 v3, v6, v7
	global_store_dwordx4 v[62:63], v[0:3], off
	s_nop 1
	v_lshlrev_b32_e32 v0, 16, v44
	v_and_b32_e32 v1, 0xffff0000, v44
	v_pk_fma_f32 v[10:11], v[24:25], v[10:11], v[0:1]
	v_lshlrev_b32_e32 v0, 16, v45
	v_and_b32_e32 v1, 0xffff0000, v45
	v_pk_fma_f32 v[4:5], v[24:25], v[4:5], v[0:1]
	v_lshlrev_b32_e32 v0, 16, v46
	v_and_b32_e32 v1, 0xffff0000, v46
	v_pk_fma_f32 v[8:9], v[24:25], v[8:9], v[0:1]
	v_lshlrev_b32_e32 v0, 16, v47
	v_and_b32_e32 v1, 0xffff0000, v47
	v_pk_fma_f32 v[6:7], v[24:25], v[6:7], v[0:1]
	v_cvt_pk_bf16_f32 v0, v10, v11
	v_cvt_pk_bf16_f32 v1, v4, v5
	v_cvt_pk_bf16_f32 v2, v8, v9
	v_cvt_pk_bf16_f32 v3, v6, v7
	global_store_dwordx4 v[64:65], v[0:3], off
	s_nop 1
	v_lshlrev_b32_e32 v0, 16, v48
	v_and_b32_e32 v1, 0xffff0000, v48
	v_pk_fma_f32 v[10:11], v[24:25], v[10:11], v[0:1]
	v_lshlrev_b32_e32 v0, 16, v49
	v_and_b32_e32 v1, 0xffff0000, v49
	v_pk_fma_f32 v[4:5], v[24:25], v[4:5], v[0:1]
	v_lshlrev_b32_e32 v0, 16, v50
	v_and_b32_e32 v1, 0xffff0000, v50
	v_pk_fma_f32 v[8:9], v[24:25], v[8:9], v[0:1]
	v_lshlrev_b32_e32 v0, 16, v51
	v_and_b32_e32 v1, 0xffff0000, v51
	v_pk_fma_f32 v[6:7], v[24:25], v[6:7], v[0:1]
	v_cvt_pk_bf16_f32 v0, v10, v11
	v_cvt_pk_bf16_f32 v1, v4, v5
	v_cvt_pk_bf16_f32 v2, v8, v9
	v_cvt_pk_bf16_f32 v3, v6, v7
	global_store_dwordx4 v[66:67], v[0:3], off
	s_nop 1
	v_lshlrev_b32_e32 v0, 16, v52
	v_and_b32_e32 v1, 0xffff0000, v52
	v_pk_fma_f32 v[28:29], v[24:25], v[10:11], v[0:1]
	v_lshlrev_b32_e32 v0, 16, v53
	v_and_b32_e32 v1, 0xffff0000, v53
	v_pk_fma_f32 v[30:31], v[24:25], v[4:5], v[0:1]
	v_lshlrev_b32_e32 v0, 16, v54
	v_and_b32_e32 v1, 0xffff0000, v54
	v_pk_fma_f32 v[32:33], v[24:25], v[8:9], v[0:1]
	v_lshlrev_b32_e32 v0, 16, v55
	v_and_b32_e32 v1, 0xffff0000, v55
	v_pk_fma_f32 v[22:23], v[24:25], v[6:7], v[0:1]
	v_cvt_pk_bf16_f32 v140, v28, v29
	v_cvt_pk_bf16_f32 v141, v30, v31
	v_cvt_pk_bf16_f32 v142, v32, v33
	v_cvt_pk_bf16_f32 v143, v22, v23
	global_store_dwordx4 v[106:107], v[140:143], off
	s_add_i32 s12, s12, -8
	s_add_i32 s13, s7, 8
	s_mov_b32 s7, s13
	s_add_i32 s13, s12, 7
	v_mov_b32_e32 v0, s13
	v_mov_b32_e32 v1, s7
	v_cndmask_b32_e32 v0, v0, v1, vcc
	v_add_u32_e32 v0, v0, v43
	v_ashrrev_i32_e32 v1, 31, v0
	v_lshlrev_b64 v[0:1], 14, v[0:1]
	s_add_i32 s13, s12, 6
	s_add_i32 s14, s7, 1
	v_lshl_add_u64 v[34:35], v[26:27], 0, v[0:1]
	v_mov_b32_e32 v4, s13
	v_mov_b32_e32 v5, s14
	global_load_dwordx4 v[0:3], v[34:35], off
	v_cndmask_b32_e32 v4, v4, v5, vcc
	v_add_u32_e32 v4, v4, v43
	v_ashrrev_i32_e32 v5, 31, v4
	v_lshlrev_b64 v[4:5], 14, v[4:5]
	v_lshl_add_u64 v[36:37], v[26:27], 0, v[4:5]
	s_add_i32 s13, s12, 5
	s_add_i32 s14, s7, 2
	global_load_dwordx4 v[4:7], v[36:37], off
	v_mov_b32_e32 v8, s13
	v_mov_b32_e32 v9, s14
	v_cndmask_b32_e32 v8, v8, v9, vcc
	v_add_u32_e32 v8, v8, v43
	v_ashrrev_i32_e32 v9, 31, v8
	v_lshlrev_b64 v[8:9], 14, v[8:9]
	v_lshl_add_u64 v[38:39], v[26:27], 0, v[8:9]
	s_add_i32 s13, s12, 4
	s_add_i32 s14, s7, 3
	global_load_dwordx4 v[8:11], v[38:39], off
	v_mov_b32_e32 v12, s13
	v_mov_b32_e32 v13, s14
	v_cndmask_b32_e32 v12, v12, v13, vcc
	v_add_u32_e32 v12, v12, v43
	v_ashrrev_i32_e32 v13, 31, v12
	v_lshlrev_b64 v[12:13], 14, v[12:13]
	v_lshl_add_u64 v[40:41], v[26:27], 0, v[12:13]
	s_add_i32 s13, s12, 3
	s_add_i32 s14, s7, 4
	global_load_dwordx4 v[12:15], v[40:41], off
	v_mov_b32_e32 v16, s13
	v_mov_b32_e32 v17, s14
	v_cndmask_b32_e32 v16, v16, v17, vcc
	v_add_u32_e32 v16, v16, v43
	v_ashrrev_i32_e32 v17, 31, v16
	v_lshlrev_b64 v[16:17], 14, v[16:17]
	v_lshl_add_u64 v[60:61], v[26:27], 0, v[16:17]
	s_add_i32 s13, s12, 2
	s_add_i32 s14, s7, 5
	global_load_dwordx4 v[16:19], v[60:61], off
	v_mov_b32_e32 v44, s13
	v_mov_b32_e32 v45, s14
	v_cndmask_b32_e32 v44, v44, v45, vcc
	v_add_u32_e32 v44, v44, v43
	v_ashrrev_i32_e32 v45, 31, v44
	v_lshlrev_b64 v[44:45], 14, v[44:45]
	v_lshl_add_u64 v[62:63], v[26:27], 0, v[44:45]
	s_add_i32 s13, s12, 1
	s_add_i32 s14, s7, 6
	global_load_dwordx4 v[44:47], v[62:63], off
	v_mov_b32_e32 v48, s13
	v_mov_b32_e32 v49, s14
	v_cndmask_b32_e32 v48, v48, v49, vcc
	v_add_u32_e32 v48, v48, v43
	v_ashrrev_i32_e32 v49, 31, v48
	v_lshlrev_b64 v[48:49], 14, v[48:49]
	v_lshl_add_u64 v[64:65], v[26:27], 0, v[48:49]
	s_add_i32 s13, s7, 7
	global_load_dwordx4 v[48:51], v[64:65], off
	v_mov_b32_e32 v52, s12
	v_mov_b32_e32 v53, s13
	v_cndmask_b32_e32 v52, v52, v53, vcc
	v_add_u32_e32 v52, v52, v43
	v_ashrrev_i32_e32 v53, 31, v52
	v_lshlrev_b64 v[52:53], 14, v[52:53]
	v_lshl_add_u64 v[66:67], v[26:27], 0, v[52:53]
	global_load_dwordx4 v[52:55], v[66:67], off
	s_waitcnt vmcnt(16)
	v_lshlrev_b32_e32 v106, 16, v72
	v_and_b32_e32 v107, 0xffff0000, v72
	v_lshlrev_b32_e32 v72, 16, v73
	v_and_b32_e32 v73, 0xffff0000, v73
	v_pk_fma_f32 v[30:31], v[24:25], v[30:31], v[72:73]
	v_lshlrev_b32_e32 v72, 16, v74
	v_and_b32_e32 v73, 0xffff0000, v74
	v_pk_fma_f32 v[32:33], v[24:25], v[32:33], v[72:73]
	v_lshlrev_b32_e32 v72, 16, v75
	v_and_b32_e32 v73, 0xffff0000, v75
	v_pk_fma_f32 v[28:29], v[24:25], v[28:29], v[106:107]
	v_pk_fma_f32 v[22:23], v[24:25], v[22:23], v[72:73]
	v_cvt_pk_bf16_f32 v72, v28, v29
	v_cvt_pk_bf16_f32 v73, v30, v31
	v_cvt_pk_bf16_f32 v74, v32, v33
	v_cvt_pk_bf16_f32 v75, v22, v23
	global_store_dwordx4 v[108:109], v[72:75], off
	s_nop 1
	v_lshlrev_b32_e32 v72, 16, v76
	v_and_b32_e32 v73, 0xffff0000, v76
	v_pk_fma_f32 v[28:29], v[24:25], v[28:29], v[72:73]
	v_lshlrev_b32_e32 v72, 16, v77
	v_and_b32_e32 v73, 0xffff0000, v77
	v_pk_fma_f32 v[76:77], v[24:25], v[30:31], v[72:73]
	v_lshlrev_b32_e32 v72, 16, v78
	v_and_b32_e32 v73, 0xffff0000, v78
	v_pk_fma_f32 v[30:31], v[24:25], v[32:33], v[72:73]
	v_lshlrev_b32_e32 v72, 16, v79
	v_and_b32_e32 v73, 0xffff0000, v79
	v_pk_fma_f32 v[78:79], v[24:25], v[22:23], v[72:73]
	v_cvt_pk_bf16_f32 v72, v28, v29
	v_cvt_pk_bf16_f32 v73, v76, v77
	v_cvt_pk_bf16_f32 v74, v30, v31
	v_cvt_pk_bf16_f32 v75, v78, v79
	global_store_dwordx4 v[110:111], v[72:75], off
	s_nop 1
	v_lshlrev_b32_e32 v72, 16, v80
	v_and_b32_e32 v73, 0xffff0000, v80
	v_pk_fma_f32 v[22:23], v[24:25], v[28:29], v[72:73]
	v_lshlrev_b32_e32 v72, 16, v81
	v_and_b32_e32 v73, 0xffff0000, v81
	v_pk_fma_f32 v[76:77], v[24:25], v[76:77], v[72:73]
	v_lshlrev_b32_e32 v72, 16, v82
	v_and_b32_e32 v73, 0xffff0000, v82
	v_pk_fma_f32 v[80:81], v[24:25], v[30:31], v[72:73]
	v_lshlrev_b32_e32 v72, 16, v83
	v_and_b32_e32 v73, 0xffff0000, v83
	v_pk_fma_f32 v[78:79], v[24:25], v[78:79], v[72:73]
	v_cvt_pk_bf16_f32 v72, v22, v23
	v_cvt_pk_bf16_f32 v73, v76, v77
	v_cvt_pk_bf16_f32 v74, v80, v81
	v_cvt_pk_bf16_f32 v75, v78, v79
	global_store_dwordx4 v[112:113], v[72:75], off
	s_nop 1
	v_lshlrev_b32_e32 v72, 16, v84
	v_and_b32_e32 v73, 0xffff0000, v84
	v_pk_fma_f32 v[82:83], v[24:25], v[22:23], v[72:73]
	v_lshlrev_b32_e32 v72, 16, v85
	v_and_b32_e32 v73, 0xffff0000, v85
	v_pk_fma_f32 v[76:77], v[24:25], v[76:77], v[72:73]
	v_lshlrev_b32_e32 v72, 16, v86
	v_and_b32_e32 v73, 0xffff0000, v86
	v_pk_fma_f32 v[80:81], v[24:25], v[80:81], v[72:73]
	v_lshlrev_b32_e32 v72, 16, v87
	v_and_b32_e32 v73, 0xffff0000, v87
	v_pk_fma_f32 v[78:79], v[24:25], v[78:79], v[72:73]
	v_cvt_pk_bf16_f32 v72, v82, v83
	v_cvt_pk_bf16_f32 v73, v76, v77
	v_cvt_pk_bf16_f32 v74, v80, v81
	v_cvt_pk_bf16_f32 v75, v78, v79
	global_store_dwordx4 v[144:145], v[72:75], off
	s_nop 1
	v_lshlrev_b32_e32 v72, 16, v88
	v_and_b32_e32 v73, 0xffff0000, v88
	v_pk_fma_f32 v[82:83], v[24:25], v[82:83], v[72:73]
	v_lshlrev_b32_e32 v72, 16, v89
	v_and_b32_e32 v73, 0xffff0000, v89
	v_pk_fma_f32 v[76:77], v[24:25], v[76:77], v[72:73]
	v_lshlrev_b32_e32 v72, 16, v90
	v_and_b32_e32 v73, 0xffff0000, v90
	v_pk_fma_f32 v[80:81], v[24:25], v[80:81], v[72:73]
	v_lshlrev_b32_e32 v72, 16, v91
	v_and_b32_e32 v73, 0xffff0000, v91
	v_pk_fma_f32 v[78:79], v[24:25], v[78:79], v[72:73]
	v_cvt_pk_bf16_f32 v72, v82, v83
	v_cvt_pk_bf16_f32 v73, v76, v77
	v_cvt_pk_bf16_f32 v74, v80, v81
	v_cvt_pk_bf16_f32 v75, v78, v79
	global_store_dwordx4 v[146:147], v[72:75], off
	s_nop 1
	v_lshlrev_b32_e32 v72, 16, v116
	v_and_b32_e32 v73, 0xffff0000, v116
	v_pk_fma_f32 v[82:83], v[24:25], v[82:83], v[72:73]
	v_lshlrev_b32_e32 v72, 16, v117
	v_and_b32_e32 v73, 0xffff0000, v117
	v_pk_fma_f32 v[76:77], v[24:25], v[76:77], v[72:73]
	v_lshlrev_b32_e32 v72, 16, v118
	v_and_b32_e32 v73, 0xffff0000, v118
	v_pk_fma_f32 v[80:81], v[24:25], v[80:81], v[72:73]
	v_lshlrev_b32_e32 v72, 16, v119
	v_and_b32_e32 v73, 0xffff0000, v119
	v_pk_fma_f32 v[78:79], v[24:25], v[78:79], v[72:73]
	v_cvt_pk_bf16_f32 v72, v82, v83
	v_cvt_pk_bf16_f32 v73, v76, v77
	v_cvt_pk_bf16_f32 v74, v80, v81
	v_cvt_pk_bf16_f32 v75, v78, v79
	global_store_dwordx4 v[148:149], v[72:75], off
	s_nop 1
	v_lshlrev_b32_e32 v72, 16, v120
	v_and_b32_e32 v73, 0xffff0000, v120
	v_pk_fma_f32 v[82:83], v[24:25], v[82:83], v[72:73]
	v_lshlrev_b32_e32 v72, 16, v121
	v_and_b32_e32 v73, 0xffff0000, v121
	v_pk_fma_f32 v[76:77], v[24:25], v[76:77], v[72:73]
	v_lshlrev_b32_e32 v72, 16, v122
	v_and_b32_e32 v73, 0xffff0000, v122
	v_pk_fma_f32 v[80:81], v[24:25], v[80:81], v[72:73]
	v_lshlrev_b32_e32 v72, 16, v123
	v_and_b32_e32 v73, 0xffff0000, v123
	v_pk_fma_f32 v[78:79], v[24:25], v[78:79], v[72:73]
	v_cvt_pk_bf16_f32 v72, v82, v83
	v_cvt_pk_bf16_f32 v73, v76, v77
	v_cvt_pk_bf16_f32 v74, v80, v81
	v_cvt_pk_bf16_f32 v75, v78, v79
	global_store_dwordx4 v[150:151], v[72:75], off
	s_nop 1
	v_lshlrev_b32_e32 v72, 16, v124
	v_and_b32_e32 v73, 0xffff0000, v124
	v_pk_fma_f32 v[28:29], v[24:25], v[82:83], v[72:73]
	v_lshlrev_b32_e32 v72, 16, v125
	v_and_b32_e32 v73, 0xffff0000, v125
	v_pk_fma_f32 v[30:31], v[24:25], v[76:77], v[72:73]
	v_lshlrev_b32_e32 v72, 16, v126
	v_and_b32_e32 v73, 0xffff0000, v126
	v_pk_fma_f32 v[32:33], v[24:25], v[80:81], v[72:73]
	v_lshlrev_b32_e32 v72, 16, v127
	v_and_b32_e32 v73, 0xffff0000, v127
	v_pk_fma_f32 v[22:23], v[24:25], v[78:79], v[72:73]
	v_cvt_pk_bf16_f32 v56, v28, v29
	v_cvt_pk_bf16_f32 v57, v30, v31
	v_cvt_pk_bf16_f32 v58, v32, v33
	v_cvt_pk_bf16_f32 v59, v22, v23
	global_store_dwordx4 v[34:35], v[56:59], off
	s_add_i32 s12, s12, -8
	s_add_i32 s13, s7, 8
	s_mov_b32 s7, s13
	s_add_i32 s13, s12, 7
	v_mov_b32_e32 v72, s13
	v_mov_b32_e32 v73, s7
	v_cndmask_b32_e32 v72, v72, v73, vcc
	v_add_u32_e32 v72, v72, v43
	v_ashrrev_i32_e32 v73, 31, v72
	v_lshlrev_b64 v[72:73], 14, v[72:73]
	s_add_i32 s13, s12, 6
	s_add_i32 s14, s7, 1
	v_lshl_add_u64 v[106:107], v[26:27], 0, v[72:73]
	v_mov_b32_e32 v76, s13
	v_mov_b32_e32 v77, s14
	global_load_dwordx4 v[72:75], v[106:107], off
	v_cndmask_b32_e32 v76, v76, v77, vcc
	v_add_u32_e32 v76, v76, v43
	v_ashrrev_i32_e32 v77, 31, v76
	v_lshlrev_b64 v[76:77], 14, v[76:77]
	v_lshl_add_u64 v[108:109], v[26:27], 0, v[76:77]
	s_add_i32 s13, s12, 5
	s_add_i32 s14, s7, 2
	global_load_dwordx4 v[76:79], v[108:109], off
	v_mov_b32_e32 v80, s13
	v_mov_b32_e32 v81, s14
	v_cndmask_b32_e32 v80, v80, v81, vcc
	v_add_u32_e32 v80, v80, v43
	v_ashrrev_i32_e32 v81, 31, v80
	v_lshlrev_b64 v[80:81], 14, v[80:81]
	v_lshl_add_u64 v[110:111], v[26:27], 0, v[80:81]
	s_add_i32 s13, s12, 4
	s_add_i32 s14, s7, 3
	global_load_dwordx4 v[80:83], v[110:111], off
	v_mov_b32_e32 v84, s13
	v_mov_b32_e32 v85, s14
	v_cndmask_b32_e32 v84, v84, v85, vcc
	v_add_u32_e32 v84, v84, v43
	v_ashrrev_i32_e32 v85, 31, v84
	v_lshlrev_b64 v[84:85], 14, v[84:85]
	v_lshl_add_u64 v[112:113], v[26:27], 0, v[84:85]
	s_add_i32 s13, s12, 3
	s_add_i32 s14, s7, 4
	global_load_dwordx4 v[84:87], v[112:113], off
	v_mov_b32_e32 v88, s13
	v_mov_b32_e32 v89, s14
	v_cndmask_b32_e32 v88, v88, v89, vcc
	v_add_u32_e32 v88, v88, v43
	v_ashrrev_i32_e32 v89, 31, v88
	v_lshlrev_b64 v[88:89], 14, v[88:89]
	v_lshl_add_u64 v[144:145], v[26:27], 0, v[88:89]
	s_add_i32 s13, s12, 2
	s_add_i32 s14, s7, 5
	global_load_dwordx4 v[88:91], v[144:145], off
	v_mov_b32_e32 v116, s13
	v_mov_b32_e32 v117, s14
	v_cndmask_b32_e32 v116, v116, v117, vcc
	v_add_u32_e32 v116, v116, v43
	v_ashrrev_i32_e32 v117, 31, v116
	v_lshlrev_b64 v[116:117], 14, v[116:117]
	v_lshl_add_u64 v[146:147], v[26:27], 0, v[116:117]
	s_add_i32 s13, s12, 1
	s_add_i32 s14, s7, 6
	global_load_dwordx4 v[116:119], v[146:147], off
	v_mov_b32_e32 v120, s13
	v_mov_b32_e32 v121, s14
	v_cndmask_b32_e32 v120, v120, v121, vcc
	v_add_u32_e32 v120, v120, v43
	v_ashrrev_i32_e32 v121, 31, v120
	v_lshlrev_b64 v[120:121], 14, v[120:121]
	v_lshl_add_u64 v[148:149], v[26:27], 0, v[120:121]
	s_add_i32 s13, s7, 7
	global_load_dwordx4 v[120:123], v[148:149], off
	v_mov_b32_e32 v124, s12
	v_mov_b32_e32 v125, s13
	v_cndmask_b32_e32 v124, v124, v125, vcc
	v_add_u32_e32 v124, v124, v43
	v_ashrrev_i32_e32 v125, 31, v124
	v_lshlrev_b64 v[124:125], 14, v[124:125]
	v_lshl_add_u64 v[150:151], v[26:27], 0, v[124:125]
	global_load_dwordx4 v[124:127], v[150:151], off
	s_waitcnt vmcnt(16)
	v_lshlrev_b32_e32 v34, 16, v0
	v_and_b32_e32 v35, 0xffff0000, v0
	v_lshlrev_b32_e32 v0, 16, v1
	v_and_b32_e32 v1, 0xffff0000, v1
	v_pk_fma_f32 v[30:31], v[24:25], v[30:31], v[0:1]
	v_lshlrev_b32_e32 v0, 16, v2
	v_and_b32_e32 v1, 0xffff0000, v2
	v_pk_fma_f32 v[32:33], v[24:25], v[32:33], v[0:1]
	v_lshlrev_b32_e32 v0, 16, v3
	v_and_b32_e32 v1, 0xffff0000, v3
	v_pk_fma_f32 v[28:29], v[24:25], v[28:29], v[34:35]
	v_pk_fma_f32 v[22:23], v[24:25], v[22:23], v[0:1]
	v_cvt_pk_bf16_f32 v0, v28, v29
	v_cvt_pk_bf16_f32 v1, v30, v31
	v_cvt_pk_bf16_f32 v2, v32, v33
	v_cvt_pk_bf16_f32 v3, v22, v23
	global_store_dwordx4 v[36:37], v[0:3], off
	s_nop 1
	v_lshlrev_b32_e32 v0, 16, v4
	v_and_b32_e32 v1, 0xffff0000, v4
	v_pk_fma_f32 v[28:29], v[24:25], v[28:29], v[0:1]
	v_lshlrev_b32_e32 v0, 16, v5
	v_and_b32_e32 v1, 0xffff0000, v5
	v_pk_fma_f32 v[4:5], v[24:25], v[30:31], v[0:1]
	v_lshlrev_b32_e32 v0, 16, v6
	v_and_b32_e32 v1, 0xffff0000, v6
	v_pk_fma_f32 v[30:31], v[24:25], v[32:33], v[0:1]
	v_lshlrev_b32_e32 v0, 16, v7
	v_and_b32_e32 v1, 0xffff0000, v7
	v_pk_fma_f32 v[6:7], v[24:25], v[22:23], v[0:1]
	v_cvt_pk_bf16_f32 v0, v28, v29
	v_cvt_pk_bf16_f32 v1, v4, v5
	v_cvt_pk_bf16_f32 v2, v30, v31
	v_cvt_pk_bf16_f32 v3, v6, v7
	global_store_dwordx4 v[38:39], v[0:3], off
	s_nop 1
	v_lshlrev_b32_e32 v0, 16, v8
	v_and_b32_e32 v1, 0xffff0000, v8
	v_pk_fma_f32 v[22:23], v[24:25], v[28:29], v[0:1]
	v_lshlrev_b32_e32 v0, 16, v9
	v_and_b32_e32 v1, 0xffff0000, v9
	v_pk_fma_f32 v[4:5], v[24:25], v[4:5], v[0:1]
	v_lshlrev_b32_e32 v0, 16, v10
	v_and_b32_e32 v1, 0xffff0000, v10
	v_pk_fma_f32 v[8:9], v[24:25], v[30:31], v[0:1]
	v_lshlrev_b32_e32 v0, 16, v11
	v_and_b32_e32 v1, 0xffff0000, v11
	v_pk_fma_f32 v[6:7], v[24:25], v[6:7], v[0:1]
	v_cvt_pk_bf16_f32 v0, v22, v23
	v_cvt_pk_bf16_f32 v1, v4, v5
	v_cvt_pk_bf16_f32 v2, v8, v9
	v_cvt_pk_bf16_f32 v3, v6, v7
	global_store_dwordx4 v[40:41], v[0:3], off
	s_nop 1
	v_lshlrev_b32_e32 v0, 16, v12
	v_and_b32_e32 v1, 0xffff0000, v12
	v_pk_fma_f32 v[10:11], v[24:25], v[22:23], v[0:1]
	v_lshlrev_b32_e32 v0, 16, v13
	v_and_b32_e32 v1, 0xffff0000, v13
	v_pk_fma_f32 v[4:5], v[24:25], v[4:5], v[0:1]
	v_lshlrev_b32_e32 v0, 16, v14
	v_and_b32_e32 v1, 0xffff0000, v14
	v_pk_fma_f32 v[8:9], v[24:25], v[8:9], v[0:1]
	v_lshlrev_b32_e32 v0, 16, v15
	v_and_b32_e32 v1, 0xffff0000, v15
	v_pk_fma_f32 v[6:7], v[24:25], v[6:7], v[0:1]
	v_cvt_pk_bf16_f32 v0, v10, v11
	v_cvt_pk_bf16_f32 v1, v4, v5
	v_cvt_pk_bf16_f32 v2, v8, v9
	v_cvt_pk_bf16_f32 v3, v6, v7
	global_store_dwordx4 v[60:61], v[0:3], off
	s_nop 1
	v_lshlrev_b32_e32 v0, 16, v16
	v_and_b32_e32 v1, 0xffff0000, v16
	v_pk_fma_f32 v[10:11], v[24:25], v[10:11], v[0:1]
	v_lshlrev_b32_e32 v0, 16, v17
	v_and_b32_e32 v1, 0xffff0000, v17
	v_pk_fma_f32 v[4:5], v[24:25], v[4:5], v[0:1]
	v_lshlrev_b32_e32 v0, 16, v18
	v_and_b32_e32 v1, 0xffff0000, v18
	v_pk_fma_f32 v[8:9], v[24:25], v[8:9], v[0:1]
	v_lshlrev_b32_e32 v0, 16, v19
	v_and_b32_e32 v1, 0xffff0000, v19
	v_pk_fma_f32 v[6:7], v[24:25], v[6:7], v[0:1]
	v_cvt_pk_bf16_f32 v0, v10, v11
	v_cvt_pk_bf16_f32 v1, v4, v5
	v_cvt_pk_bf16_f32 v2, v8, v9
	v_cvt_pk_bf16_f32 v3, v6, v7
	global_store_dwordx4 v[62:63], v[0:3], off
	s_nop 1
	v_lshlrev_b32_e32 v0, 16, v44
	v_and_b32_e32 v1, 0xffff0000, v44
	v_pk_fma_f32 v[10:11], v[24:25], v[10:11], v[0:1]
	v_lshlrev_b32_e32 v0, 16, v45
	v_and_b32_e32 v1, 0xffff0000, v45
	v_pk_fma_f32 v[4:5], v[24:25], v[4:5], v[0:1]
	v_lshlrev_b32_e32 v0, 16, v46
	v_and_b32_e32 v1, 0xffff0000, v46
	v_pk_fma_f32 v[8:9], v[24:25], v[8:9], v[0:1]
	v_lshlrev_b32_e32 v0, 16, v47
	v_and_b32_e32 v1, 0xffff0000, v47
	v_pk_fma_f32 v[6:7], v[24:25], v[6:7], v[0:1]
	v_cvt_pk_bf16_f32 v0, v10, v11
	v_cvt_pk_bf16_f32 v1, v4, v5
	v_cvt_pk_bf16_f32 v2, v8, v9
	v_cvt_pk_bf16_f32 v3, v6, v7
	global_store_dwordx4 v[64:65], v[0:3], off
	s_nop 1
	v_lshlrev_b32_e32 v0, 16, v48
	v_and_b32_e32 v1, 0xffff0000, v48
	v_pk_fma_f32 v[10:11], v[24:25], v[10:11], v[0:1]
	v_lshlrev_b32_e32 v0, 16, v49
	v_and_b32_e32 v1, 0xffff0000, v49
	v_pk_fma_f32 v[4:5], v[24:25], v[4:5], v[0:1]
	v_lshlrev_b32_e32 v0, 16, v50
	v_and_b32_e32 v1, 0xffff0000, v50
	v_pk_fma_f32 v[8:9], v[24:25], v[8:9], v[0:1]
	v_lshlrev_b32_e32 v0, 16, v51
	v_and_b32_e32 v1, 0xffff0000, v51
	v_pk_fma_f32 v[6:7], v[24:25], v[6:7], v[0:1]
	v_cvt_pk_bf16_f32 v0, v10, v11
	v_cvt_pk_bf16_f32 v1, v4, v5
	v_cvt_pk_bf16_f32 v2, v8, v9
	v_cvt_pk_bf16_f32 v3, v6, v7
	global_store_dwordx4 v[66:67], v[0:3], off
	s_nop 1
	v_lshlrev_b32_e32 v0, 16, v52
	v_and_b32_e32 v1, 0xffff0000, v52
	v_pk_fma_f32 v[28:29], v[24:25], v[10:11], v[0:1]
	v_lshlrev_b32_e32 v0, 16, v53
	v_and_b32_e32 v1, 0xffff0000, v53
	v_pk_fma_f32 v[30:31], v[24:25], v[4:5], v[0:1]
	v_lshlrev_b32_e32 v0, 16, v54
	v_and_b32_e32 v1, 0xffff0000, v54
	v_pk_fma_f32 v[32:33], v[24:25], v[8:9], v[0:1]
	v_lshlrev_b32_e32 v0, 16, v55
	v_and_b32_e32 v1, 0xffff0000, v55
	v_pk_fma_f32 v[22:23], v[24:25], v[6:7], v[0:1]
	v_cvt_pk_bf16_f32 v140, v28, v29
	v_cvt_pk_bf16_f32 v141, v30, v31
	v_cvt_pk_bf16_f32 v142, v32, v33
	v_cvt_pk_bf16_f32 v143, v22, v23
	global_store_dwordx4 v[106:107], v[140:143], off
	s_add_i32 s12, s12, -8
	s_add_i32 s13, s7, 8
	s_mov_b32 s7, s13
	s_waitcnt vmcnt(8)
	v_lshlrev_b32_e32 v106, 16, v72
	v_and_b32_e32 v107, 0xffff0000, v72
	v_lshlrev_b32_e32 v72, 16, v73
	v_and_b32_e32 v73, 0xffff0000, v73
	v_pk_fma_f32 v[30:31], v[24:25], v[30:31], v[72:73]
	v_lshlrev_b32_e32 v72, 16, v74
	v_and_b32_e32 v73, 0xffff0000, v74
	v_pk_fma_f32 v[32:33], v[24:25], v[32:33], v[72:73]
	v_lshlrev_b32_e32 v72, 16, v75
	v_and_b32_e32 v73, 0xffff0000, v75
	v_pk_fma_f32 v[28:29], v[24:25], v[28:29], v[106:107]
	v_pk_fma_f32 v[22:23], v[24:25], v[22:23], v[72:73]
	v_cvt_pk_bf16_f32 v72, v28, v29
	v_cvt_pk_bf16_f32 v73, v30, v31
	v_cvt_pk_bf16_f32 v74, v32, v33
	v_cvt_pk_bf16_f32 v75, v22, v23
	global_store_dwordx4 v[108:109], v[72:75], off
	s_nop 1
	v_lshlrev_b32_e32 v72, 16, v76
	v_and_b32_e32 v73, 0xffff0000, v76
	v_pk_fma_f32 v[28:29], v[24:25], v[28:29], v[72:73]
	v_lshlrev_b32_e32 v72, 16, v77
	v_and_b32_e32 v73, 0xffff0000, v77
	v_pk_fma_f32 v[76:77], v[24:25], v[30:31], v[72:73]
	v_lshlrev_b32_e32 v72, 16, v78
	v_and_b32_e32 v73, 0xffff0000, v78
	v_pk_fma_f32 v[30:31], v[24:25], v[32:33], v[72:73]
	v_lshlrev_b32_e32 v72, 16, v79
	v_and_b32_e32 v73, 0xffff0000, v79
	v_pk_fma_f32 v[78:79], v[24:25], v[22:23], v[72:73]
	v_cvt_pk_bf16_f32 v72, v28, v29
	v_cvt_pk_bf16_f32 v73, v76, v77
	v_cvt_pk_bf16_f32 v74, v30, v31
	v_cvt_pk_bf16_f32 v75, v78, v79
	global_store_dwordx4 v[110:111], v[72:75], off
	s_nop 1
	v_lshlrev_b32_e32 v72, 16, v80
	v_and_b32_e32 v73, 0xffff0000, v80
	v_pk_fma_f32 v[22:23], v[24:25], v[28:29], v[72:73]
	v_lshlrev_b32_e32 v72, 16, v81
	v_and_b32_e32 v73, 0xffff0000, v81
	v_pk_fma_f32 v[76:77], v[24:25], v[76:77], v[72:73]
	v_lshlrev_b32_e32 v72, 16, v82
	v_and_b32_e32 v73, 0xffff0000, v82
	v_pk_fma_f32 v[80:81], v[24:25], v[30:31], v[72:73]
	v_lshlrev_b32_e32 v72, 16, v83
	v_and_b32_e32 v73, 0xffff0000, v83
	v_pk_fma_f32 v[78:79], v[24:25], v[78:79], v[72:73]
	v_cvt_pk_bf16_f32 v72, v22, v23
	v_cvt_pk_bf16_f32 v73, v76, v77
	v_cvt_pk_bf16_f32 v74, v80, v81
	v_cvt_pk_bf16_f32 v75, v78, v79
	global_store_dwordx4 v[112:113], v[72:75], off
	s_nop 1
	v_lshlrev_b32_e32 v72, 16, v84
	v_and_b32_e32 v73, 0xffff0000, v84
	v_pk_fma_f32 v[82:83], v[24:25], v[22:23], v[72:73]
	v_lshlrev_b32_e32 v72, 16, v85
	v_and_b32_e32 v73, 0xffff0000, v85
	v_pk_fma_f32 v[76:77], v[24:25], v[76:77], v[72:73]
	v_lshlrev_b32_e32 v72, 16, v86
	v_and_b32_e32 v73, 0xffff0000, v86
	v_pk_fma_f32 v[80:81], v[24:25], v[80:81], v[72:73]
	v_lshlrev_b32_e32 v72, 16, v87
	v_and_b32_e32 v73, 0xffff0000, v87
	v_pk_fma_f32 v[78:79], v[24:25], v[78:79], v[72:73]
	v_cvt_pk_bf16_f32 v72, v82, v83
	v_cvt_pk_bf16_f32 v73, v76, v77
	v_cvt_pk_bf16_f32 v74, v80, v81
	v_cvt_pk_bf16_f32 v75, v78, v79
	global_store_dwordx4 v[144:145], v[72:75], off
	s_nop 1
	v_lshlrev_b32_e32 v72, 16, v88
	v_and_b32_e32 v73, 0xffff0000, v88
	v_pk_fma_f32 v[82:83], v[24:25], v[82:83], v[72:73]
	v_lshlrev_b32_e32 v72, 16, v89
	v_and_b32_e32 v73, 0xffff0000, v89
	v_pk_fma_f32 v[76:77], v[24:25], v[76:77], v[72:73]
	v_lshlrev_b32_e32 v72, 16, v90
	v_and_b32_e32 v73, 0xffff0000, v90
	v_pk_fma_f32 v[80:81], v[24:25], v[80:81], v[72:73]
	v_lshlrev_b32_e32 v72, 16, v91
	v_and_b32_e32 v73, 0xffff0000, v91
	v_pk_fma_f32 v[78:79], v[24:25], v[78:79], v[72:73]
	v_cvt_pk_bf16_f32 v72, v82, v83
	v_cvt_pk_bf16_f32 v73, v76, v77
	v_cvt_pk_bf16_f32 v74, v80, v81
	v_cvt_pk_bf16_f32 v75, v78, v79
	global_store_dwordx4 v[146:147], v[72:75], off
	s_nop 1
	v_lshlrev_b32_e32 v72, 16, v116
	v_and_b32_e32 v73, 0xffff0000, v116
	v_pk_fma_f32 v[82:83], v[24:25], v[82:83], v[72:73]
	v_lshlrev_b32_e32 v72, 16, v117
	v_and_b32_e32 v73, 0xffff0000, v117
	v_pk_fma_f32 v[76:77], v[24:25], v[76:77], v[72:73]
	v_lshlrev_b32_e32 v72, 16, v118
	v_and_b32_e32 v73, 0xffff0000, v118
	v_pk_fma_f32 v[80:81], v[24:25], v[80:81], v[72:73]
	v_lshlrev_b32_e32 v72, 16, v119
	v_and_b32_e32 v73, 0xffff0000, v119
	v_pk_fma_f32 v[78:79], v[24:25], v[78:79], v[72:73]
	v_cvt_pk_bf16_f32 v72, v82, v83
	v_cvt_pk_bf16_f32 v73, v76, v77
	v_cvt_pk_bf16_f32 v74, v80, v81
	v_cvt_pk_bf16_f32 v75, v78, v79
	global_store_dwordx4 v[148:149], v[72:75], off
	s_nop 1
	v_lshlrev_b32_e32 v72, 16, v120
	v_and_b32_e32 v73, 0xffff0000, v120
	v_pk_fma_f32 v[82:83], v[24:25], v[82:83], v[72:73]
	v_lshlrev_b32_e32 v72, 16, v121
	v_and_b32_e32 v73, 0xffff0000, v121
	v_pk_fma_f32 v[76:77], v[24:25], v[76:77], v[72:73]
	v_lshlrev_b32_e32 v72, 16, v122
	v_and_b32_e32 v73, 0xffff0000, v122
	v_pk_fma_f32 v[80:81], v[24:25], v[80:81], v[72:73]
	v_lshlrev_b32_e32 v72, 16, v123
	v_and_b32_e32 v73, 0xffff0000, v123
	v_pk_fma_f32 v[78:79], v[24:25], v[78:79], v[72:73]
	v_cvt_pk_bf16_f32 v72, v82, v83
	v_cvt_pk_bf16_f32 v73, v76, v77
	v_cvt_pk_bf16_f32 v74, v80, v81
	v_cvt_pk_bf16_f32 v75, v78, v79
	global_store_dwordx4 v[150:151], v[72:75], off
	s_nop 1
	v_lshlrev_b32_e32 v72, 16, v124
	v_and_b32_e32 v73, 0xffff0000, v124
	v_pk_fma_f32 v[28:29], v[24:25], v[82:83], v[72:73]
	v_lshlrev_b32_e32 v72, 16, v125
	v_and_b32_e32 v73, 0xffff0000, v125
	v_pk_fma_f32 v[30:31], v[24:25], v[76:77], v[72:73]
	v_lshlrev_b32_e32 v72, 16, v126
	v_and_b32_e32 v73, 0xffff0000, v126
	v_pk_fma_f32 v[32:33], v[24:25], v[80:81], v[72:73]
	v_lshlrev_b32_e32 v72, 16, v127
	v_and_b32_e32 v73, 0xffff0000, v127
	v_pk_fma_f32 v[22:23], v[24:25], v[78:79], v[72:73]
	v_add_u32_e32 v42, s6, v42
	s_mov_b32 s7, 0xbfff
	v_cmp_lt_i32_e32 vcc, s7, v42
	s_or_b64 s[2:3], vcc, s[2:3]
	s_andn2_b64 exec, exec, s[2:3]
	s_cbranch_execnz .LBB0_209
	s_or_b64 exec, exec, s[2:3]
	s_load_dword s2, s[38:39], 0x0
	s_waitcnt lgkmcnt(0)
	v_mov_b32_e32 v1, s2

.LBB0_216:
	s_add_i32 s12, s7, 7
	v_mov_b32_e32 v4, s12
	v_mov_b32_e32 v5, s6
	v_cndmask_b32_e32 v4, v4, v5, vcc
	v_add_u32_e32 v38, v4, v49
	v_ashrrev_i32_e32 v39, 31, v38
	v_lshlrev_b64 v[8:9], 6, v[38:39]
	v_or_b32_e32 v8, v8, v34
	v_lshlrev_b64 v[4:5], 8, v[8:9]
	v_lshl_add_u64 v[4:5], v[32:33], 0, v[4:5]
	v_lshl_add_u64 v[8:9], v[8:9], 2, s[30:31]
	s_add_i32 s12, s7, 6
	s_add_i32 s13, s6, 1
	global_load_dwordx4 v[4:7], v[4:5], off
	v_mov_b32_e32 v53, s7
	global_load_dword v40, v[8:9], off
	v_mov_b32_e32 v8, s12
	v_mov_b32_e32 v9, s13
	v_cndmask_b32_e32 v8, v8, v9, vcc
	v_add_u32_e32 v42, v8, v49
	v_ashrrev_i32_e32 v43, 31, v42
	v_lshlrev_b64 v[12:13], 6, v[42:43]
	v_or_b32_e32 v12, v12, v34
	v_lshlrev_b64 v[8:9], 8, v[12:13]
	v_lshl_add_u64 v[8:9], v[32:33], 0, v[8:9]
	v_lshl_add_u64 v[12:13], v[12:13], 2, s[30:31]
	s_add_i32 s12, s7, 5
	s_add_i32 s13, s6, 2
	global_load_dwordx4 v[8:11], v[8:9], off
	v_lshlrev_b64 v[38:39], 14, v[38:39]
	global_load_dword v44, v[12:13], off
	v_mov_b32_e32 v12, s12
	v_mov_b32_e32 v13, s13
	v_cndmask_b32_e32 v12, v12, v13, vcc
	v_add_u32_e32 v46, v12, v49
	v_ashrrev_i32_e32 v47, 31, v46
	v_lshlrev_b64 v[16:17], 6, v[46:47]
	v_or_b32_e32 v16, v16, v34
	v_lshlrev_b64 v[12:13], 8, v[16:17]
	v_lshl_add_u64 v[12:13], v[32:33], 0, v[12:13]
	v_lshl_add_u64 v[16:17], v[16:17], 2, s[30:31]
	s_add_i32 s12, s7, 4
	s_add_i32 s13, s6, 3
	global_load_dwordx4 v[12:15], v[12:13], off
	v_lshl_add_u64 v[38:39], v[36:37], 0, v[38:39]
	global_load_dword v48, v[16:17], off
	v_mov_b32_e32 v16, s12
	v_mov_b32_e32 v17, s13
	v_cndmask_b32_e32 v16, v16, v17, vcc
	v_add_u32_e32 v50, v16, v49
	v_ashrrev_i32_e32 v51, 31, v50
	v_lshlrev_b64 v[20:21], 6, v[50:51]
	v_or_b32_e32 v20, v20, v34
	v_lshlrev_b64 v[16:17], 8, v[20:21]
	v_lshl_add_u64 v[16:17], v[32:33], 0, v[16:17]
	v_lshl_add_u64 v[20:21], v[20:21], 2, s[30:31]
	s_add_i32 s12, s7, 3
	s_add_i32 s13, s6, 4
	global_load_dwordx4 v[16:19], v[16:17], off
	s_nop 0
	global_load_dword v52, v[20:21], off
	v_mov_b32_e32 v20, s12
	v_mov_b32_e32 v21, s13
	v_cndmask_b32_e32 v20, v20, v21, vcc
	v_add_u32_e32 v54, v20, v49
	v_ashrrev_i32_e32 v55, 31, v54
	v_lshlrev_b64 v[24:25], 6, v[54:55]
	v_or_b32_e32 v24, v24, v34
	v_lshlrev_b64 v[20:21], 8, v[24:25]
	v_lshl_add_u64 v[20:21], v[32:33], 0, v[20:21]
	v_lshl_add_u64 v[24:25], v[24:25], 2, s[30:31]
	s_add_i32 s12, s7, 2
	s_add_i32 s13, s6, 5
	global_load_dwordx4 v[20:23], v[20:21], off
	s_nop 0
	global_load_dword v56, v[24:25], off
	v_mov_b32_e32 v24, s12
	v_mov_b32_e32 v25, s13
	v_cndmask_b32_e32 v24, v24, v25, vcc
	v_add_u32_e32 v58, v24, v49
	v_ashrrev_i32_e32 v59, 31, v58
	v_lshlrev_b64 v[28:29], 6, v[58:59]
	v_or_b32_e32 v28, v28, v34
	v_lshlrev_b64 v[24:25], 8, v[28:29]
	v_lshl_add_u64 v[24:25], v[32:33], 0, v[24:25]
	v_lshl_add_u64 v[28:29], v[28:29], 2, s[30:31]
	s_add_i32 s12, s7, 1
	s_add_i32 s13, s6, 6
	global_load_dwordx4 v[24:27], v[24:25], off
	s_add_i32 s7, s7, -8
	global_load_dword v60, v[28:29], off
	v_mov_b32_e32 v28, s12
	v_mov_b32_e32 v29, s13
	s_add_i32 s12, s6, 7
	v_cndmask_b32_e32 v28, v28, v29, vcc
	v_mov_b32_e32 v57, s12
	v_add_u32_e32 v62, v28, v49
	v_cndmask_b32_e32 v53, v53, v57, vcc
	v_ashrrev_i32_e32 v63, 31, v62
	v_add_u32_e32 v66, v53, v49
	v_lshlrev_b64 v[64:65], 6, v[62:63]
	v_ashrrev_i32_e32 v67, 31, v66
	v_or_b32_e32 v64, v64, v34
	v_lshlrev_b64 v[72:73], 6, v[66:67]
	v_lshlrev_b64 v[28:29], 8, v[64:65]
	v_or_b32_e32 v72, v72, v34
	v_lshl_add_u64 v[28:29], v[32:33], 0, v[28:29]
	v_lshl_add_u64 v[64:65], v[64:65], 2, s[30:31]
	v_lshlrev_b64 v[68:69], 8, v[72:73]
	global_load_dwordx4 v[28:31], v[28:29], off
	v_lshl_add_u64 v[68:69], v[32:33], 0, v[68:69]
	global_load_dword v64, v[64:65], off
	v_lshl_add_u64 v[72:73], v[72:73], 2, s[30:31]
	global_load_dwordx4 v[68:71], v[68:69], off
	s_add_i32 s12, s6, 8
	global_load_dword v72, v[72:73], off
	global_store_dwordx4 v[38:39], v[0:3], off
	s_mov_b32 s6, s12
	s_add_i32 s12, s7, 7
	v_mov_b32_e32 v76, s12
	v_mov_b32_e32 v77, s6
	v_cndmask_b32_e32 v76, v76, v77, vcc
	v_add_u32_e32 v110, v76, v49
	v_ashrrev_i32_e32 v111, 31, v110
	v_lshlrev_b64 v[80:81], 6, v[110:111]
	v_or_b32_e32 v80, v80, v34
	v_lshlrev_b64 v[76:77], 8, v[80:81]
	v_lshl_add_u64 v[76:77], v[32:33], 0, v[76:77]
	v_lshl_add_u64 v[80:81], v[80:81], 2, s[30:31]
	s_add_i32 s12, s7, 6
	s_add_i32 s13, s6, 1
	global_load_dwordx4 v[76:79], v[76:77], off
	v_mov_b32_e32 v125, s7
	global_load_dword v112, v[80:81], off
	v_mov_b32_e32 v80, s12
	v_mov_b32_e32 v81, s13
	v_cndmask_b32_e32 v80, v80, v81, vcc
	v_add_u32_e32 v114, v80, v49
	v_ashrrev_i32_e32 v115, 31, v114
	v_lshlrev_b64 v[84:85], 6, v[114:115]
	v_or_b32_e32 v84, v84, v34
	v_lshlrev_b64 v[80:81], 8, v[84:85]
	v_lshl_add_u64 v[80:81], v[32:33], 0, v[80:81]
	v_lshl_add_u64 v[84:85], v[84:85], 2, s[30:31]
	s_add_i32 s12, s7, 5
	s_add_i32 s13, s6, 2
	global_load_dwordx4 v[80:83], v[80:81], off
	v_lshlrev_b64 v[110:111], 14, v[110:111]
	global_load_dword v116, v[84:85], off
	v_mov_b32_e32 v84, s12
	v_mov_b32_e32 v85, s13
	v_cndmask_b32_e32 v84, v84, v85, vcc
	v_add_u32_e32 v118, v84, v49
	v_ashrrev_i32_e32 v119, 31, v118
	v_lshlrev_b64 v[88:89], 6, v[118:119]
	v_or_b32_e32 v88, v88, v34
	v_lshlrev_b64 v[84:85], 8, v[88:89]
	v_lshl_add_u64 v[84:85], v[32:33], 0, v[84:85]
	v_lshl_add_u64 v[88:89], v[88:89], 2, s[30:31]
	s_add_i32 s12, s7, 4
	s_add_i32 s13, s6, 3
	global_load_dwordx4 v[84:87], v[84:85], off
	v_lshl_add_u64 v[110:111], v[36:37], 0, v[110:111]
	global_load_dword v120, v[88:89], off
	v_mov_b32_e32 v88, s12
	v_mov_b32_e32 v89, s13
	v_cndmask_b32_e32 v88, v88, v89, vcc
	v_add_u32_e32 v122, v88, v49
	v_ashrrev_i32_e32 v123, 31, v122
	v_lshlrev_b64 v[92:93], 6, v[122:123]
	v_or_b32_e32 v92, v92, v34
	v_lshlrev_b64 v[88:89], 8, v[92:93]
	v_lshl_add_u64 v[88:89], v[32:33], 0, v[88:89]
	v_lshl_add_u64 v[92:93], v[92:93], 2, s[30:31]
	s_add_i32 s12, s7, 3
	s_add_i32 s13, s6, 4
	global_load_dwordx4 v[88:91], v[88:89], off
	s_nop 0
	global_load_dword v124, v[92:93], off
	v_mov_b32_e32 v92, s12
	v_mov_b32_e32 v93, s13
	v_cndmask_b32_e32 v92, v92, v93, vcc
	v_add_u32_e32 v126, v92, v49
	v_ashrrev_i32_e32 v127, 31, v126
	v_lshlrev_b64 v[96:97], 6, v[126:127]
	v_or_b32_e32 v96, v96, v34
	v_lshlrev_b64 v[92:93], 8, v[96:97]
	v_lshl_add_u64 v[92:93], v[32:33], 0, v[92:93]
	v_lshl_add_u64 v[96:97], v[96:97], 2, s[30:31]
	s_add_i32 s12, s7, 2
	s_add_i32 s13, s6, 5
	global_load_dwordx4 v[92:95], v[92:93], off
	s_nop 0
	global_load_dword v140, v[96:97], off
	v_mov_b32_e32 v96, s12
	v_mov_b32_e32 v97, s13
	v_cndmask_b32_e32 v96, v96, v97, vcc
	v_add_u32_e32 v142, v96, v49
	v_ashrrev_i32_e32 v143, 31, v142
	v_lshlrev_b64 v[100:101], 6, v[142:143]
	v_or_b32_e32 v100, v100, v34
	v_lshlrev_b64 v[96:97], 8, v[100:101]
	v_lshl_add_u64 v[96:97], v[32:33], 0, v[96:97]
	v_lshl_add_u64 v[100:101], v[100:101], 2, s[30:31]
	s_add_i32 s12, s7, 1
	s_add_i32 s13, s6, 6
	global_load_dwordx4 v[96:99], v[96:97], off
	s_add_i32 s7, s7, -8
	global_load_dword v144, v[100:101], off
	v_mov_b32_e32 v100, s12
	v_mov_b32_e32 v101, s13
	s_add_i32 s12, s6, 7
	v_cndmask_b32_e32 v100, v100, v101, vcc
	v_mov_b32_e32 v141, s12
	v_add_u32_e32 v146, v100, v49
	v_cndmask_b32_e32 v125, v125, v141, vcc
	v_ashrrev_i32_e32 v147, 31, v146
	v_add_u32_e32 v150, v125, v49
	v_lshlrev_b64 v[148:149], 6, v[146:147]
	v_ashrrev_i32_e32 v151, 31, v150
	v_or_b32_e32 v148, v148, v34
	v_lshlrev_b64 v[156:157], 6, v[150:151]
	v_lshlrev_b64 v[100:101], 8, v[148:149]
	v_or_b32_e32 v156, v156, v34
	v_lshl_add_u64 v[100:101], v[32:33], 0, v[100:101]
	v_lshl_add_u64 v[148:149], v[148:149], 2, s[30:31]
	v_lshlrev_b64 v[152:153], 8, v[156:157]
	global_load_dwordx4 v[100:103], v[100:101], off
	v_lshl_add_u64 v[152:153], v[32:33], 0, v[152:153]
	global_load_dword v148, v[148:149], off
	v_lshl_add_u64 v[156:157], v[156:157], 2, s[30:31]
	global_load_dwordx4 v[152:155], v[152:153], off
	s_add_i32 s12, s6, 8
	global_load_dword v156, v[156:157], off
	s_waitcnt vmcnt(17)
	v_pk_fma_f32 v[0:1], v[0:1], v[40:41], v[4:5] op_sel_hi:[1,0,1]
	v_lshlrev_b64 v[4:5], 14, v[42:43]
	v_pk_fma_f32 v[2:3], v[2:3], v[40:41], v[6:7] op_sel_hi:[1,0,1]
	v_lshl_add_u64 v[4:5], v[36:37], 0, v[4:5]
	global_store_dwordx4 v[4:5], v[0:3], off
	v_lshlrev_b64 v[4:5], 14, v[46:47]
	v_lshl_add_u64 v[4:5], v[36:37], 0, v[4:5]
	v_pk_fma_f32 v[0:1], v[0:1], v[44:45], v[8:9] op_sel_hi:[1,0,1]
	v_pk_fma_f32 v[2:3], v[2:3], v[44:45], v[10:11] op_sel_hi:[1,0,1]
	global_store_dwordx4 v[4:5], v[0:3], off
	v_lshlrev_b64 v[4:5], 14, v[50:51]
	v_lshl_add_u64 v[4:5], v[36:37], 0, v[4:5]
	v_pk_fma_f32 v[0:1], v[0:1], v[48:49], v[12:13] op_sel_hi:[1,0,1]
	v_pk_fma_f32 v[2:3], v[2:3], v[48:49], v[14:15] op_sel_hi:[1,0,1]
	global_store_dwordx4 v[4:5], v[0:3], off
	v_lshlrev_b64 v[4:5], 14, v[54:55]
	v_lshl_add_u64 v[4:5], v[36:37], 0, v[4:5]
	v_pk_fma_f32 v[0:1], v[0:1], v[52:53], v[16:17] op_sel_hi:[1,0,1]
	v_pk_fma_f32 v[2:3], v[2:3], v[52:53], v[18:19] op_sel_hi:[1,0,1]
	global_store_dwordx4 v[4:5], v[0:3], off
	v_lshlrev_b64 v[4:5], 14, v[58:59]
	v_lshl_add_u64 v[4:5], v[36:37], 0, v[4:5]
	v_pk_fma_f32 v[0:1], v[0:1], v[56:57], v[20:21] op_sel_hi:[1,0,1]
	v_pk_fma_f32 v[2:3], v[2:3], v[56:57], v[22:23] op_sel_hi:[1,0,1]
	global_store_dwordx4 v[4:5], v[0:3], off
	v_lshlrev_b64 v[4:5], 14, v[62:63]
	v_lshl_add_u64 v[4:5], v[36:37], 0, v[4:5]
	v_pk_fma_f32 v[0:1], v[0:1], v[60:61], v[24:25] op_sel_hi:[1,0,1]
	v_pk_fma_f32 v[2:3], v[2:3], v[60:61], v[26:27] op_sel_hi:[1,0,1]
	global_store_dwordx4 v[4:5], v[0:3], off
	v_lshlrev_b64 v[4:5], 14, v[66:67]
	v_lshl_add_u64 v[4:5], v[36:37], 0, v[4:5]
	v_pk_fma_f32 v[0:1], v[0:1], v[64:65], v[28:29] op_sel_hi:[1,0,1]
	v_pk_fma_f32 v[2:3], v[2:3], v[64:65], v[30:31] op_sel_hi:[1,0,1]
	global_store_dwordx4 v[4:5], v[0:3], off
	s_nop 1
	v_pk_fma_f32 v[2:3], v[2:3], v[72:73], v[70:71] op_sel_hi:[1,0,1]
	v_pk_fma_f32 v[0:1], v[0:1], v[72:73], v[68:69] op_sel_hi:[1,0,1]
	global_store_dwordx4 v[110:111], v[0:3], off
	s_mov_b32 s6, s12
	s_add_i32 s12, s7, 7
	v_mov_b32_e32 v4, s12
	v_mov_b32_e32 v5, s6
	v_cndmask_b32_e32 v4, v4, v5, vcc
	v_add_u32_e32 v38, v4, v49
	v_ashrrev_i32_e32 v39, 31, v38
	v_lshlrev_b64 v[8:9], 6, v[38:39]
	v_or_b32_e32 v8, v8, v34
	v_lshlrev_b64 v[4:5], 8, v[8:9]
	v_lshl_add_u64 v[4:5], v[32:33], 0, v[4:5]
	v_lshl_add_u64 v[8:9], v[8:9], 2, s[30:31]
	s_add_i32 s12, s7, 6
	s_add_i32 s13, s6, 1
	global_load_dwordx4 v[4:7], v[4:5], off
	v_mov_b32_e32 v53, s7
	global_load_dword v40, v[8:9], off
	v_mov_b32_e32 v8, s12
	v_mov_b32_e32 v9, s13
	v_cndmask_b32_e32 v8, v8, v9, vcc
	v_add_u32_e32 v42, v8, v49
	v_ashrrev_i32_e32 v43, 31, v42
	v_lshlrev_b64 v[12:13], 6, v[42:43]
	v_or_b32_e32 v12, v12, v34
	v_lshlrev_b64 v[8:9], 8, v[12:13]
	v_lshl_add_u64 v[8:9], v[32:33], 0, v[8:9]
	v_lshl_add_u64 v[12:13], v[12:13], 2, s[30:31]
	s_add_i32 s12, s7, 5
	s_add_i32 s13, s6, 2
	global_load_dwordx4 v[8:11], v[8:9], off
	v_lshlrev_b64 v[38:39], 14, v[38:39]
	global_load_dword v44, v[12:13], off
	v_mov_b32_e32 v12, s12
	v_mov_b32_e32 v13, s13
	v_cndmask_b32_e32 v12, v12, v13, vcc
	v_add_u32_e32 v46, v12, v49
	v_ashrrev_i32_e32 v47, 31, v46
	v_lshlrev_b64 v[16:17], 6, v[46:47]
	v_or_b32_e32 v16, v16, v34
	v_lshlrev_b64 v[12:13], 8, v[16:17]
	v_lshl_add_u64 v[12:13], v[32:33], 0, v[12:13]
	v_lshl_add_u64 v[16:17], v[16:17], 2, s[30:31]
	s_add_i32 s12, s7, 4
	s_add_i32 s13, s6, 3
	global_load_dwordx4 v[12:15], v[12:13], off
	v_lshl_add_u64 v[38:39], v[36:37], 0, v[38:39]
	global_load_dword v48, v[16:17], off
	v_mov_b32_e32 v16, s12
	v_mov_b32_e32 v17, s13
	v_cndmask_b32_e32 v16, v16, v17, vcc
	v_add_u32_e32 v50, v16, v49
	v_ashrrev_i32_e32 v51, 31, v50
	v_lshlrev_b64 v[20:21], 6, v[50:51]
	v_or_b32_e32 v20, v20, v34
	v_lshlrev_b64 v[16:17], 8, v[20:21]
	v_lshl_add_u64 v[16:17], v[32:33], 0, v[16:17]
	v_lshl_add_u64 v[20:21], v[20:21], 2, s[30:31]
	s_add_i32 s12, s7, 3
	s_add_i32 s13, s6, 4
	global_load_dwordx4 v[16:19], v[16:17], off
	s_nop 0
	global_load_dword v52, v[20:21], off
	v_mov_b32_e32 v20, s12
	v_mov_b32_e32 v21, s13
	v_cndmask_b32_e32 v20, v20, v21, vcc
	v_add_u32_e32 v54, v20, v49
	v_ashrrev_i32_e32 v55, 31, v54
	v_lshlrev_b64 v[24:25], 6, v[54:55]
	v_or_b32_e32 v24, v24, v34
	v_lshlrev_b64 v[20:21], 8, v[24:25]
	v_lshl_add_u64 v[20:21], v[32:33], 0, v[20:21]
	v_lshl_add_u64 v[24:25], v[24:25], 2, s[30:31]
	s_add_i32 s12, s7, 2
	s_add_i32 s13, s6, 5
	global_load_dwordx4 v[20:23], v[20:21], off
	s_nop 0
	global_load_dword v56, v[24:25], off
	v_mov_b32_e32 v24, s12
	v_mov_b32_e32 v25, s13
	v_cndmask_b32_e32 v24, v24, v25, vcc
	v_add_u32_e32 v58, v24, v49
	v_ashrrev_i32_e32 v59, 31, v58
	v_lshlrev_b64 v[28:29], 6, v[58:59]
	v_or_b32_e32 v28, v28, v34
	v_lshlrev_b64 v[24:25], 8, v[28:29]
	v_lshl_add_u64 v[24:25], v[32:33], 0, v[24:25]
	v_lshl_add_u64 v[28:29], v[28:29], 2, s[30:31]
	s_add_i32 s12, s7, 1
	s_add_i32 s13, s6, 6
	global_load_dwordx4 v[24:27], v[24:25], off
	s_add_i32 s7, s7, -8
	global_load_dword v60, v[28:29], off
	v_mov_b32_e32 v28, s12
	v_mov_b32_e32 v29, s13
	s_add_i32 s12, s6, 7
	v_cndmask_b32_e32 v28, v28, v29, vcc
	v_mov_b32_e32 v57, s12
	v_add_u32_e32 v62, v28, v49
	v_cndmask_b32_e32 v53, v53, v57, vcc
	v_ashrrev_i32_e32 v63, 31, v62
	v_add_u32_e32 v66, v53, v49
	v_lshlrev_b64 v[64:65], 6, v[62:63]
	v_ashrrev_i32_e32 v67, 31, v66
	v_or_b32_e32 v64, v64, v34
	v_lshlrev_b64 v[72:73], 6, v[66:67]
	v_lshlrev_b64 v[28:29], 8, v[64:65]
	v_or_b32_e32 v72, v72, v34
	v_lshl_add_u64 v[28:29], v[32:33], 0, v[28:29]
	v_lshl_add_u64 v[64:65], v[64:65], 2, s[30:31]
	v_lshlrev_b64 v[68:69], 8, v[72:73]
	global_load_dwordx4 v[28:31], v[28:29], off
	v_lshl_add_u64 v[68:69], v[32:33], 0, v[68:69]
	global_load_dword v64, v[64:65], off
	v_lshl_add_u64 v[72:73], v[72:73], 2, s[30:31]
	global_load_dwordx4 v[68:71], v[68:69], off
	s_add_i32 s12, s6, 8
	global_load_dword v72, v[72:73], off
	s_waitcnt vmcnt(24)
	v_pk_fma_f32 v[0:1], v[0:1], v[112:113], v[76:77] op_sel_hi:[1,0,1]
	v_lshlrev_b64 v[76:77], 14, v[114:115]
	v_pk_fma_f32 v[2:3], v[2:3], v[112:113], v[78:79] op_sel_hi:[1,0,1]
	v_lshl_add_u64 v[76:77], v[36:37], 0, v[76:77]
	global_store_dwordx4 v[76:77], v[0:3], off
	v_lshlrev_b64 v[76:77], 14, v[118:119]
	v_lshl_add_u64 v[76:77], v[36:37], 0, v[76:77]
	v_pk_fma_f32 v[0:1], v[0:1], v[116:117], v[80:81] op_sel_hi:[1,0,1]
	v_pk_fma_f32 v[2:3], v[2:3], v[116:117], v[82:83] op_sel_hi:[1,0,1]
	global_store_dwordx4 v[76:77], v[0:3], off
	v_lshlrev_b64 v[76:77], 14, v[122:123]
	v_lshl_add_u64 v[76:77], v[36:37], 0, v[76:77]
	v_pk_fma_f32 v[0:1], v[0:1], v[120:121], v[84:85] op_sel_hi:[1,0,1]
	v_pk_fma_f32 v[2:3], v[2:3], v[120:121], v[86:87] op_sel_hi:[1,0,1]
	global_store_dwordx4 v[76:77], v[0:3], off
	v_lshlrev_b64 v[76:77], 14, v[126:127]
	v_lshl_add_u64 v[76:77], v[36:37], 0, v[76:77]
	v_pk_fma_f32 v[0:1], v[0:1], v[124:125], v[88:89] op_sel_hi:[1,0,1]
	v_pk_fma_f32 v[2:3], v[2:3], v[124:125], v[90:91] op_sel_hi:[1,0,1]
	global_store_dwordx4 v[76:77], v[0:3], off
	v_lshlrev_b64 v[76:77], 14, v[142:143]
	v_lshl_add_u64 v[76:77], v[36:37], 0, v[76:77]
	v_pk_fma_f32 v[0:1], v[0:1], v[140:141], v[92:93] op_sel_hi:[1,0,1]
	v_pk_fma_f32 v[2:3], v[2:3], v[140:141], v[94:95] op_sel_hi:[1,0,1]
	global_store_dwordx4 v[76:77], v[0:3], off
	v_lshlrev_b64 v[76:77], 14, v[146:147]
	v_lshl_add_u64 v[76:77], v[36:37], 0, v[76:77]
	v_pk_fma_f32 v[0:1], v[0:1], v[144:145], v[96:97] op_sel_hi:[1,0,1]
	v_pk_fma_f32 v[2:3], v[2:3], v[144:145], v[98:99] op_sel_hi:[1,0,1]
	global_store_dwordx4 v[76:77], v[0:3], off
	v_lshlrev_b64 v[76:77], 14, v[150:151]
	v_lshl_add_u64 v[76:77], v[36:37], 0, v[76:77]
	v_pk_fma_f32 v[0:1], v[0:1], v[148:149], v[100:101] op_sel_hi:[1,0,1]
	v_pk_fma_f32 v[2:3], v[2:3], v[148:149], v[102:103] op_sel_hi:[1,0,1]
	global_store_dwordx4 v[76:77], v[0:3], off
	s_nop 1
	v_pk_fma_f32 v[2:3], v[2:3], v[156:157], v[154:155] op_sel_hi:[1,0,1]
	v_pk_fma_f32 v[0:1], v[0:1], v[156:157], v[152:153] op_sel_hi:[1,0,1]
	global_store_dwordx4 v[38:39], v[0:3], off
	s_mov_b32 s6, s12
	s_add_i32 s12, s7, 7
	v_mov_b32_e32 v76, s12
	v_mov_b32_e32 v77, s6
	v_cndmask_b32_e32 v76, v76, v77, vcc
	v_add_u32_e32 v110, v76, v49
	v_ashrrev_i32_e32 v111, 31, v110
	v_lshlrev_b64 v[80:81], 6, v[110:111]
	v_or_b32_e32 v80, v80, v34
	v_lshlrev_b64 v[76:77], 8, v[80:81]
	v_lshl_add_u64 v[76:77], v[32:33], 0, v[76:77]
	v_lshl_add_u64 v[80:81], v[80:81], 2, s[30:31]
	s_add_i32 s12, s7, 6
	s_add_i32 s13, s6, 1
	global_load_dwordx4 v[76:79], v[76:77], off
	v_mov_b32_e32 v125, s7
	global_load_dword v112, v[80:81], off
	v_mov_b32_e32 v80, s12
	v_mov_b32_e32 v81, s13
	v_cndmask_b32_e32 v80, v80, v81, vcc
	v_add_u32_e32 v114, v80, v49
	v_ashrrev_i32_e32 v115, 31, v114
	v_lshlrev_b64 v[84:85], 6, v[114:115]
	v_or_b32_e32 v84, v84, v34
	v_lshlrev_b64 v[80:81], 8, v[84:85]
	v_lshl_add_u64 v[80:81], v[32:33], 0, v[80:81]
	v_lshl_add_u64 v[84:85], v[84:85], 2, s[30:31]
	s_add_i32 s12, s7, 5
	s_add_i32 s13, s6, 2
	global_load_dwordx4 v[80:83], v[80:81], off
	v_lshlrev_b64 v[110:111], 14, v[110:111]
	global_load_dword v116, v[84:85], off
	v_mov_b32_e32 v84, s12
	v_mov_b32_e32 v85, s13
	v_cndmask_b32_e32 v84, v84, v85, vcc
	v_add_u32_e32 v118, v84, v49
	v_ashrrev_i32_e32 v119, 31, v118
	v_lshlrev_b64 v[88:89], 6, v[118:119]
	v_or_b32_e32 v88, v88, v34
	v_lshlrev_b64 v[84:85], 8, v[88:89]
	v_lshl_add_u64 v[84:85], v[32:33], 0, v[84:85]
	v_lshl_add_u64 v[88:89], v[88:89], 2, s[30:31]
	s_add_i32 s12, s7, 4
	s_add_i32 s13, s6, 3
	global_load_dwordx4 v[84:87], v[84:85], off
	v_lshl_add_u64 v[110:111], v[36:37], 0, v[110:111]
	global_load_dword v120, v[88:89], off
	v_mov_b32_e32 v88, s12
	v_mov_b32_e32 v89, s13
	v_cndmask_b32_e32 v88, v88, v89, vcc
	v_add_u32_e32 v122, v88, v49
	v_ashrrev_i32_e32 v123, 31, v122
	v_lshlrev_b64 v[92:93], 6, v[122:123]
	v_or_b32_e32 v92, v92, v34
	v_lshlrev_b64 v[88:89], 8, v[92:93]
	v_lshl_add_u64 v[88:89], v[32:33], 0, v[88:89]
	v_lshl_add_u64 v[92:93], v[92:93], 2, s[30:31]
	s_add_i32 s12, s7, 3
	s_add_i32 s13, s6, 4
	global_load_dwordx4 v[88:91], v[88:89], off
	s_nop 0
	global_load_dword v124, v[92:93], off
	v_mov_b32_e32 v92, s12
	v_mov_b32_e32 v93, s13
	v_cndmask_b32_e32 v92, v92, v93, vcc
	v_add_u32_e32 v126, v92, v49
	v_ashrrev_i32_e32 v127, 31, v126
	v_lshlrev_b64 v[96:97], 6, v[126:127]
	v_or_b32_e32 v96, v96, v34
	v_lshlrev_b64 v[92:93], 8, v[96:97]
	v_lshl_add_u64 v[92:93], v[32:33], 0, v[92:93]
	v_lshl_add_u64 v[96:97], v[96:97], 2, s[30:31]
	s_add_i32 s12, s7, 2
	s_add_i32 s13, s6, 5
	global_load_dwordx4 v[92:95], v[92:93], off
	s_nop 0
	global_load_dword v140, v[96:97], off
	v_mov_b32_e32 v96, s12
	v_mov_b32_e32 v97, s13
	v_cndmask_b32_e32 v96, v96, v97, vcc
	v_add_u32_e32 v142, v96, v49
	v_ashrrev_i32_e32 v143, 31, v142
	v_lshlrev_b64 v[100:101], 6, v[142:143]
	v_or_b32_e32 v100, v100, v34
	v_lshlrev_b64 v[96:97], 8, v[100:101]
	v_lshl_add_u64 v[96:97], v[32:33], 0, v[96:97]
	v_lshl_add_u64 v[100:101], v[100:101], 2, s[30:31]
	s_add_i32 s12, s7, 1
	s_add_i32 s13, s6, 6
	global_load_dwordx4 v[96:99], v[96:97], off
	s_add_i32 s7, s7, -8
	global_load_dword v144, v[100:101], off
	v_mov_b32_e32 v100, s12
	v_mov_b32_e32 v101, s13
	s_add_i32 s12, s6, 7
	v_cndmask_b32_e32 v100, v100, v101, vcc
	v_mov_b32_e32 v141, s12
	v_add_u32_e32 v146, v100, v49
	v_cndmask_b32_e32 v125, v125, v141, vcc
	v_ashrrev_i32_e32 v147, 31, v146
	v_add_u32_e32 v150, v125, v49
	v_lshlrev_b64 v[148:149], 6, v[146:147]
	v_ashrrev_i32_e32 v151, 31, v150
	v_or_b32_e32 v148, v148, v34
	v_lshlrev_b64 v[156:157], 6, v[150:151]
	v_lshlrev_b64 v[100:101], 8, v[148:149]
	v_or_b32_e32 v156, v156, v34
	v_lshl_add_u64 v[100:101], v[32:33], 0, v[100:101]
	v_lshl_add_u64 v[148:149], v[148:149], 2, s[30:31]
	v_lshlrev_b64 v[152:153], 8, v[156:157]
	global_load_dwordx4 v[100:103], v[100:101], off
	v_lshl_add_u64 v[152:153], v[32:33], 0, v[152:153]
	global_load_dword v148, v[148:149], off
	v_lshl_add_u64 v[156:157], v[156:157], 2, s[30:31]
	global_load_dwordx4 v[152:155], v[152:153], off
	s_add_i32 s12, s6, 8
	global_load_dword v156, v[156:157], off
	s_waitcnt vmcnt(24)
	v_pk_fma_f32 v[0:1], v[0:1], v[40:41], v[4:5] op_sel_hi:[1,0,1]
	v_lshlrev_b64 v[4:5], 14, v[42:43]
	v_pk_fma_f32 v[2:3], v[2:3], v[40:41], v[6:7] op_sel_hi:[1,0,1]
	v_lshl_add_u64 v[4:5], v[36:37], 0, v[4:5]
	global_store_dwordx4 v[4:5], v[0:3], off
	v_lshlrev_b64 v[4:5], 14, v[46:47]
	v_lshl_add_u64 v[4:5], v[36:37], 0, v[4:5]
	v_pk_fma_f32 v[0:1], v[0:1], v[44:45], v[8:9] op_sel_hi:[1,0,1]
	v_pk_fma_f32 v[2:3], v[2:3], v[44:45], v[10:11] op_sel_hi:[1,0,1]
	global_store_dwordx4 v[4:5], v[0:3], off
	v_lshlrev_b64 v[4:5], 14, v[50:51]
	v_lshl_add_u64 v[4:5], v[36:37], 0, v[4:5]
	v_pk_fma_f32 v[0:1], v[0:1], v[48:49], v[12:13] op_sel_hi:[1,0,1]
	v_pk_fma_f32 v[2:3], v[2:3], v[48:49], v[14:15] op_sel_hi:[1,0,1]
	global_store_dwordx4 v[4:5], v[0:3], off
	v_lshlrev_b64 v[4:5], 14, v[54:55]
	v_lshl_add_u64 v[4:5], v[36:37], 0, v[4:5]
	v_pk_fma_f32 v[0:1], v[0:1], v[52:53], v[16:17] op_sel_hi:[1,0,1]
	v_pk_fma_f32 v[2:3], v[2:3], v[52:53], v[18:19] op_sel_hi:[1,0,1]
	global_store_dwordx4 v[4:5], v[0:3], off
	v_lshlrev_b64 v[4:5], 14, v[58:59]
	v_lshl_add_u64 v[4:5], v[36:37], 0, v[4:5]
	v_pk_fma_f32 v[0:1], v[0:1], v[56:57], v[20:21] op_sel_hi:[1,0,1]
	v_pk_fma_f32 v[2:3], v[2:3], v[56:57], v[22:23] op_sel_hi:[1,0,1]
	global_store_dwordx4 v[4:5], v[0:3], off
	v_lshlrev_b64 v[4:5], 14, v[62:63]
	v_lshl_add_u64 v[4:5], v[36:37], 0, v[4:5]
	v_pk_fma_f32 v[0:1], v[0:1], v[60:61], v[24:25] op_sel_hi:[1,0,1]
	v_pk_fma_f32 v[2:3], v[2:3], v[60:61], v[26:27] op_sel_hi:[1,0,1]
	global_store_dwordx4 v[4:5], v[0:3], off
	v_lshlrev_b64 v[4:5], 14, v[66:67]
	v_lshl_add_u64 v[4:5], v[36:37], 0, v[4:5]
	v_pk_fma_f32 v[0:1], v[0:1], v[64:65], v[28:29] op_sel_hi:[1,0,1]
	v_pk_fma_f32 v[2:3], v[2:3], v[64:65], v[30:31] op_sel_hi:[1,0,1]
	global_store_dwordx4 v[4:5], v[0:3], off
	s_nop 1
	v_pk_fma_f32 v[2:3], v[2:3], v[72:73], v[70:71] op_sel_hi:[1,0,1]
	v_pk_fma_f32 v[0:1], v[0:1], v[72:73], v[68:69] op_sel_hi:[1,0,1]
	global_store_dwordx4 v[110:111], v[0:3], off
	s_mov_b32 s6, s12
	s_waitcnt vmcnt(8)
	v_pk_fma_f32 v[0:1], v[0:1], v[112:113], v[76:77] op_sel_hi:[1,0,1]
	v_lshlrev_b64 v[76:77], 14, v[114:115]
	v_pk_fma_f32 v[2:3], v[2:3], v[112:113], v[78:79] op_sel_hi:[1,0,1]
	v_lshl_add_u64 v[76:77], v[36:37], 0, v[76:77]
	global_store_dwordx4 v[76:77], v[0:3], off
	v_lshlrev_b64 v[76:77], 14, v[118:119]
	v_lshl_add_u64 v[76:77], v[36:37], 0, v[76:77]
	v_pk_fma_f32 v[0:1], v[0:1], v[116:117], v[80:81] op_sel_hi:[1,0,1]
	v_pk_fma_f32 v[2:3], v[2:3], v[116:117], v[82:83] op_sel_hi:[1,0,1]
	global_store_dwordx4 v[76:77], v[0:3], off
	v_lshlrev_b64 v[76:77], 14, v[122:123]
	v_lshl_add_u64 v[76:77], v[36:37], 0, v[76:77]
	v_pk_fma_f32 v[0:1], v[0:1], v[120:121], v[84:85] op_sel_hi:[1,0,1]
	v_pk_fma_f32 v[2:3], v[2:3], v[120:121], v[86:87] op_sel_hi:[1,0,1]
	global_store_dwordx4 v[76:77], v[0:3], off
	v_lshlrev_b64 v[76:77], 14, v[126:127]
	v_lshl_add_u64 v[76:77], v[36:37], 0, v[76:77]
	v_pk_fma_f32 v[0:1], v[0:1], v[124:125], v[88:89] op_sel_hi:[1,0,1]
	v_pk_fma_f32 v[2:3], v[2:3], v[124:125], v[90:91] op_sel_hi:[1,0,1]
	global_store_dwordx4 v[76:77], v[0:3], off
	v_lshlrev_b64 v[76:77], 14, v[142:143]
	v_lshl_add_u64 v[76:77], v[36:37], 0, v[76:77]
	v_pk_fma_f32 v[0:1], v[0:1], v[140:141], v[92:93] op_sel_hi:[1,0,1]
	v_pk_fma_f32 v[2:3], v[2:3], v[140:141], v[94:95] op_sel_hi:[1,0,1]
	global_store_dwordx4 v[76:77], v[0:3], off
	v_lshlrev_b64 v[76:77], 14, v[146:147]
	v_lshl_add_u64 v[76:77], v[36:37], 0, v[76:77]
	v_pk_fma_f32 v[0:1], v[0:1], v[144:145], v[96:97] op_sel_hi:[1,0,1]
	v_pk_fma_f32 v[2:3], v[2:3], v[144:145], v[98:99] op_sel_hi:[1,0,1]
	global_store_dwordx4 v[76:77], v[0:3], off
	v_lshlrev_b64 v[76:77], 14, v[150:151]
	v_lshl_add_u64 v[76:77], v[36:37], 0, v[76:77]
	v_pk_fma_f32 v[0:1], v[0:1], v[148:149], v[100:101] op_sel_hi:[1,0,1]
	v_pk_fma_f32 v[2:3], v[2:3], v[148:149], v[102:103] op_sel_hi:[1,0,1]
	global_store_dwordx4 v[76:77], v[0:3], off
	s_nop 1
	v_pk_fma_f32 v[2:3], v[2:3], v[156:157], v[154:155] op_sel_hi:[1,0,1]
	v_pk_fma_f32 v[0:1], v[0:1], v[156:157], v[152:153] op_sel_hi:[1,0,1]
	v_add_u32_e32 v45, v45, v35
	s_mov_b32 s6, 0xffff
	v_cmp_lt_i32_e32 vcc, s6, v45
	s_or_b64 s[2:3], vcc, s[2:3]
	s_andn2_b64 exec, exec, s[2:3]
	s_cbranch_execnz .LBB0_215
